# P3: step-0 barrier moved below step-A global loads (overlap the two latencies)
# speedup vs baseline: 1.1001x; 1.1001x over previous
; #define LAS __attribute__((address_space(3)))
; __device__ __forceinline__ float exp_f(float x) { return __builtin_amdgcn_exp2f(x * 1.4426950408889634f); }
; #define LBAR() do { asm volatile("s_waitcnt lgkmcnt(0)" ::: "memory"); __builtin_amdgcn_s_barrier(); asm volatile("" ::: "memory"); } while (0)
; __device__ __forceinline__ void prep_task(LAS unsigned char* lds, const PrepP& P, int task, int tid, int lane, int wave) {
;     ...
;     LBAR();
;     {
;         const int t = tid >> 3, seg = tid & 7;
;         const float beta = gcl[64 + t], gc = gcl[t], glc = gcl[63];
;         const float eg = exp_f(gc), et = exp_f(glc - gc);
;         const int tt = n * 64 + t;
;         const bf16_t* zr = P.z + (size_t)(row0 + t) * NZ + 4096 + h * 128 + seg * 16;
;         const LAS float* cw = (const LAS float*)(lds + 114688) + seg * 16;
;         u32x4 xz[3][2][4];
; #pragma unroll
;         for (int m = 0; m < 3; ++m)
; #pragma unroll
;             for (int hf = 0; hf < 2; ++hf)
; #pragma unroll
;                 for (int j = 0; j < 4; ++j) { const bool ok = tt - 3 + j >= 0; xz[m][hf][j] = *(const u32x4*)(zr + m * 1024 + hf * 8 + (ptrdiff_t)(ok ? j - 3 : 0) * NZ); if (!ok) xz[m][hf][j] = (u32x4){0u, 0u, 0u, 0u}; }
.LBB0_420:
	v_ashrrev_i32_e32 v26, 3, v55
	v_add_u32_e32 v0, s8, v26
	v_ashrrev_i32_e32 v1, 31, v0
	v_lshlrev_b64 v[0:1], 14, v[0:1]
	v_lshlrev_b32_e32 v2, 4, v55
	v_lshl_add_u64 v[0:1], v[40:41], 0, v[0:1]
	v_and_b32_e32 v60, 0x70, v2
	v_lshl_add_u64 v[0:1], v[0:1], 0, s[38:39]
	v_lshlrev_b32_e32 v152, 1, v60
	v_lshl_add_u64 v[4:5], v[0:1], 0, v[152:153]
	s_mov_b64 s[6:7], 0x13c02000
	s_and_b32 s9, s49, 0x7c0
	v_lshl_add_u64 v[6:7], v[4:5], 0, s[6:7]
	v_add_co_u32_e64 v12, s[6:7], s76, v4
	v_add_u32_e32 v27, s9, v26
	s_nop 0
	v_addc_co_u32_e64 v13, s[6:7], 0, v5, s[6:7]
	v_cmp_lt_i32_e32 vcc, 2, v27
	v_mov_b32_e32 v0, 0xffff4000
	v_cmp_lt_i32_e64 s[6:7], 0, v27
	v_cndmask_b32_e32 v8, 0, v0, vcc
	v_cmp_lt_i32_e64 s[8:9], 1, v27
	v_cndmask_b32_e64 v0, 0, -1, s[6:7]
	v_mov_b32_e32 v1, v0
	s_mov_b64 s[10:11], 0x13c03000
	v_cndmask_b32_e64 v9, 0, -1, vcc
	v_cndmask_b32_e64 v15, 0, -1, s[8:9]
	v_cndmask_b32_e64 v14, 0, v197, s[8:9]
	v_lshlrev_b64 v[24:25], 14, v[0:1]
	v_lshl_add_u64 v[32:33], v[4:5], 0, s[10:11]
	v_lshl_add_u64 v[10:11], v[6:7], 0, v[8:9]
	v_lshl_add_u64 v[28:29], v[6:7], 0, v[14:15]
	v_lshl_add_u64 v[30:31], v[6:7], 0, v[24:25]
	v_lshl_add_u64 v[4:5], v[32:33], 0, v[8:9]
	v_lshl_add_u64 v[8:9], v[32:33], 0, v[14:15]
	global_load_dwordx4 v[16:19], v[12:13], off offset:-4096
	global_load_dwordx4 v[20:23], v[10:11], off
	global_load_dwordx4 v[64:67], v[28:29], off
	global_load_dwordx4 v[68:71], v[30:31], off
	global_load_dwordx4 v[0:3], v[10:11], off offset:16
	global_load_dwordx4 v[72:75], v[10:11], off offset:2048
	global_load_dwordx4 v[76:79], v[28:29], off offset:2048
	global_load_dwordx4 v[80:83], v[30:31], off offset:2048
	global_load_dwordx4 v[94:97], v[6:7], off offset:2048
	global_load_dwordx4 v[98:101], v[10:11], off offset:2064
	global_load_dwordx4 v[102:105], v[28:29], off offset:2064
	global_load_dwordx4 v[106:109], v[30:31], off offset:2064
	global_load_dwordx4 v[110:113], v[6:7], off offset:2064
	global_load_dwordx4 v[114:117], v[4:5], off
	global_load_dwordx4 v[118:121], v[8:9], off
	v_lshl_add_u64 v[10:11], v[32:33], 0, v[24:25]
	global_load_dwordx4 v[122:125], v[10:11], off
	global_load_dwordx4 v[126:129], v[12:13], off
	s_waitcnt lgkmcnt(0)
	s_barrier
	v_lshl_add_u32 v12, v26, 2, v63
	v_add_u32_e32 v14, 0x1b8fc, v58
	ds_read2st64_b32 v[24:25], v12 offset1:1
	ds_read_b32 v12, v14
	global_load_dwordx4 v[130:133], v[4:5], off offset:16
	global_load_dwordx4 v[134:137], v[8:9], off offset:16
	v_cmp_lt_i32_e64 s[10:11], -1, v27
	s_mov_b32 s14, 0x1c000
	s_waitcnt lgkmcnt(0)
	v_sub_f32_e32 v8, v12, v24
	global_load_dwordx4 v[4:7], v[6:7], off offset:16
	v_mul_f32_e32 v62, 0x3fb8aa3b, v8
	global_load_dwordx4 v[138:141], v[10:11], off offset:16
	global_load_dwordx4 v[12:15], v[28:29], off offset:16
	s_nop 0
	global_load_dwordx4 v[8:11], v[30:31], off offset:16
	global_load_dwordx4 v[142:145], v[32:33], off offset:16
	v_mul_f32_e32 v61, 0x3fb8aa3b, v24
	v_mul_lo_u32 v164, v26, s50
	v_add_u32_e32 v57, 0x11000, v58
	s_waitcnt vmcnt(20)
	v_cndmask_b32_e64 v30, 0, v71, s[6:7]
	v_cndmask_b32_e64 v33, 0, v70, s[6:7]
	v_cndmask_b32_e64 v35, 0, v69, s[6:7]
	v_cndmask_b32_e64 v37, 0, v68, s[6:7]
	s_waitcnt vmcnt(19)
	v_cndmask_b32_e32 v24, 0, v3, vcc
	v_cndmask_b32_e32 v27, 0, v2, vcc
	v_cndmask_b32_e64 v36, 0, v16, s[10:11]
	v_lshlrev_b32_e32 v16, 2, v60
	v_add3_u32 v31, v58, v16, s14
	v_cndmask_b32_e64 v29, 0, v19, s[10:11]
	s_waitcnt vmcnt(10)
	v_cndmask_b32_e32 v148, 0, v114, vcc
	s_waitcnt vmcnt(9)
	v_cndmask_b32_e64 v152, 0, v118, s[8:9]
	v_cndmask_b32_e64 v32, 0, v18, s[10:11]
	v_cndmask_b32_e64 v34, 0, v17, s[10:11]
	v_cndmask_b32_e32 v38, 0, v23, vcc
	v_cndmask_b32_e32 v49, 0, v22, vcc
	v_cndmask_b32_e32 v51, 0, v21, vcc
	v_cndmask_b32_e32 v53, 0, v20, vcc
	v_cndmask_b32_e64 v39, 0, v67, s[8:9]
	v_cndmask_b32_e64 v50, 0, v66, s[8:9]
	v_cndmask_b32_e64 v52, 0, v65, s[8:9]
	v_cndmask_b32_e64 v59, 0, v64, s[8:9]
	v_cndmask_b32_e32 v28, 0, v1, vcc
	v_cndmask_b32_e32 v85, 0, v75, vcc
	v_cndmask_b32_e32 v87, 0, v74, vcc
	v_cndmask_b32_e32 v90, 0, v73, vcc
	v_cndmask_b32_e32 v92, 0, v72, vcc
	v_cndmask_b32_e64 v86, 0, v79, s[8:9]
	v_cndmask_b32_e64 v88, 0, v78, s[8:9]
	v_cndmask_b32_e64 v91, 0, v77, s[8:9]
	v_cndmask_b32_e64 v93, 0, v76, s[8:9]
	v_cndmask_b32_e64 v1, 0, v83, s[6:7]
	v_cndmask_b32_e64 v79, 0, v82, s[6:7]
	v_cndmask_b32_e64 v83, 0, v80, s[6:7]
	v_cndmask_b32_e64 v78, 0, v97, s[10:11]
	v_cndmask_b32_e64 v80, 0, v96, s[10:11]
	v_cndmask_b32_e64 v82, 0, v95, s[10:11]
	v_cndmask_b32_e64 v84, 0, v94, s[10:11]
	v_cndmask_b32_e32 v65, 0, v101, vcc
	v_cndmask_b32_e32 v69, 0, v100, vcc
	v_cndmask_b32_e32 v74, 0, v99, vcc
	v_cndmask_b32_e32 v76, 0, v98, vcc
	v_cndmask_b32_e64 v64, 0, v105, s[8:9]
	v_cndmask_b32_e64 v68, 0, v104, s[8:9]
	v_cndmask_b32_e64 v75, 0, v103, s[8:9]
	v_cndmask_b32_e64 v77, 0, v102, s[8:9]
	v_cndmask_b32_e64 v3, 0, v109, s[6:7]
	v_cndmask_b32_e64 v67, 0, v108, s[6:7]
	v_cndmask_b32_e64 v70, 0, v107, s[6:7]
	v_cndmask_b32_e64 v72, 0, v106, s[6:7]
	v_cndmask_b32_e64 v2, 0, v113, s[10:11]
	v_cndmask_b32_e64 v66, 0, v112, s[10:11]
	v_cndmask_b32_e64 v71, 0, v111, s[10:11]
	v_cndmask_b32_e64 v73, 0, v110, s[10:11]
	v_cndmask_b32_e32 v89, 0, v117, vcc
	v_cndmask_b32_e32 v146, 0, v116, vcc
	v_cndmask_b32_e32 v147, 0, v115, vcc
	v_cndmask_b32_e64 v149, 0, v121, s[8:9]
	v_cndmask_b32_e64 v150, 0, v120, s[8:9]
	v_cndmask_b32_e64 v151, 0, v119, s[8:9]
	s_waitcnt vmcnt(8)
	v_cndmask_b32_e64 v156, 0, v125, s[6:7]
	v_cndmask_b32_e64 v157, 0, v124, s[6:7]
	v_cndmask_b32_e64 v158, 0, v123, s[6:7]
	v_cndmask_b32_e64 v159, 0, v122, s[6:7]
	s_waitcnt vmcnt(7)
; #define LAS __attribute__((address_space(3)))
; __device__ __forceinline__ float bflo(unsigned w) { return __uint_as_float(w << 16); }
; __device__ __forceinline__ float bfhi(unsigned w) { return __uint_as_float(w & 0xffff0000u); }
; __device__ __forceinline__ float silu_f(float x) { return x * rcp_f(1.f + exp_f(-x)); }
; __device__ __forceinline__ void conv8(const u32x4 (&x)[4], const LAS float* w, float (&o)[8]) {
;     f32x4 wa[4], wb[4];
; #pragma unroll
;     for (int j = 0; j < 4; ++j) { wa[j] = *(const LAS f32x4*)(w + j * 384); wb[j] = *(const LAS f32x4*)(w + j * 384 + 4); }
; #pragma unroll
;     for (int i = 0; i < 8; ++i) o[i] = 0.f;
; #pragma unroll
;     for (int j = 0; j < 4; ++j) {
;         o[0] += wa[j].x * bflo(x[j].x); o[1] += wa[j].y * bfhi(x[j].x); o[2] += wa[j].z * bflo(x[j].y); o[3] += wa[j].w * bfhi(x[j].y);
;         o[4] += wb[j].x * bflo(x[j].z); o[5] += wb[j].y * bfhi(x[j].z); o[6] += wb[j].z * bflo(x[j].w); o[7] += wb[j].w * bfhi(x[j].w); }
; #pragma unroll
;     for (int i = 0; i < 8; ++i) o[i] = silu_f(o[i]);
; }
; __device__ __forceinline__ void prep_task(LAS unsigned char* lds, const PrepP& P, int task, int tid, int lane, int wave) {
;     ...
;         { float o[8]; conv8(xz[2][0], cw + 256, o);
; #pragma unroll
;           for (int i = 0; i < 8; ++i) x[i] = o[i] * beta;
;           conv8(xz[2][1], cw + 256 + 8, o);
; #pragma unroll
;           for (int i = 0; i < 8; ++i) x[8 + i] = o[i] * beta; }
	v_cndmask_b32_e64 v160, 0, v129, s[10:11]
	v_cndmask_b32_e64 v161, 0, v128, s[10:11]
	v_cndmask_b32_e64 v162, 0, v127, s[10:11]
	v_cndmask_b32_e64 v163, 0, v126, s[10:11]
	ds_read_b128 v[94:97], v31 offset:1024
	ds_read_b128 v[98:101], v31 offset:1040
	ds_read_b128 v[20:23], v31 offset:1056
	ds_read_b128 v[16:19], v31 offset:1072
	ds_read_b128 v[102:105], v31 offset:2560
	ds_read_b128 v[106:109], v31 offset:2576
	ds_read_b128 v[110:113], v31 offset:4096
	ds_read_b128 v[114:117], v31 offset:4112
	ds_read_b128 v[118:121], v31 offset:5632
	ds_read_b128 v[122:125], v31 offset:5648
	v_lshlrev_b32_e32 v127, 16, v152
	v_lshlrev_b32_e32 v126, 16, v148
	s_waitcnt lgkmcnt(9)
	v_mov_b32_e32 v128, v94
	s_waitcnt lgkmcnt(5)
	v_mov_b32_e32 v129, v102
	v_pk_mul_f32 v[126:127], v[128:129], v[126:127]
	v_mov_b32_e32 v102, v95
	v_add_f32_e32 v94, 0, v126
	v_add_f32_e32 v128, v94, v127
	v_and_b32_e32 v127, 0xffff0000, v152
	v_and_b32_e32 v126, 0xffff0000, v148
	v_pk_mul_f32 v[94:95], v[102:103], v[126:127]
	v_mov_b32_e32 v102, v96
	v_add_f32_e32 v94, 0, v94
	v_add_f32_e32 v126, v94, v95
	v_lshlrev_b32_e32 v95, 16, v151
	v_lshlrev_b32_e32 v94, 16, v147
	v_mov_b32_e32 v103, v104
	v_pk_mul_f32 v[94:95], v[102:103], v[94:95]
	v_mov_b32_e32 v104, v97
	v_add_f32_e32 v94, 0, v94
	v_add_f32_e32 v102, v94, v95
	v_and_b32_e32 v95, 0xffff0000, v151
	v_and_b32_e32 v94, 0xffff0000, v147
	v_pk_mul_f32 v[94:95], v[104:105], v[94:95]
	v_mov_b32_e32 v96, v98
	v_add_f32_e32 v94, 0, v94
	v_add_f32_e32 v103, v94, v95
	v_lshlrev_b32_e32 v95, 16, v150
	v_lshlrev_b32_e32 v94, 16, v146
	s_waitcnt lgkmcnt(4)
	v_mov_b32_e32 v97, v106
	v_pk_mul_f32 v[94:95], v[96:97], v[94:95]
	v_mov_b32_e32 v106, v99
	v_add_f32_e32 v94, 0, v94
	v_add_f32_e32 v98, v94, v95
	v_and_b32_e32 v95, 0xffff0000, v150
	v_and_b32_e32 v94, 0xffff0000, v146
	v_pk_mul_f32 v[94:95], v[106:107], v[94:95]
	v_mov_b32_e32 v96, v100
	v_add_f32_e32 v94, 0, v94
	v_add_f32_e32 v99, v94, v95
	v_lshlrev_b32_e32 v95, 16, v149
	v_lshlrev_b32_e32 v94, 16, v89
	v_mov_b32_e32 v97, v108
	v_pk_mul_f32 v[94:95], v[96:97], v[94:95]
	v_mov_b32_e32 v108, v101
	v_add_f32_e32 v94, 0, v94
	v_add_f32_e32 v100, v94, v95
	v_and_b32_e32 v95, 0xffff0000, v149
	v_and_b32_e32 v94, 0xffff0000, v89
	v_pk_mul_f32 v[94:95], v[108:109], v[94:95]
	s_waitcnt lgkmcnt(3)
	v_mov_b32_e32 v96, v110
	v_add_f32_e32 v89, 0, v94
	v_add_f32_e32 v89, v89, v95
	v_lshlrev_b32_e32 v94, 16, v159
	v_lshlrev_b32_e32 v95, 16, v163
	s_waitcnt lgkmcnt(1)
	v_mov_b32_e32 v97, v118
	v_pk_mul_f32 v[94:95], v[96:97], v[94:95]
	v_mov_b32_e32 v118, v111
	v_add_f32_e32 v94, v128, v94
	v_add_f32_e32 v101, v94, v95
	v_and_b32_e32 v95, 0xffff0000, v163
	v_and_b32_e32 v94, 0xffff0000, v159
	v_pk_mul_f32 v[94:95], v[118:119], v[94:95]
	v_mov_b32_e32 v96, v112
	v_add_f32_e32 v94, v126, v94
	v_add_f32_e32 v104, v94, v95
	v_lshlrev_b32_e32 v94, 16, v158
	v_lshlrev_b32_e32 v95, 16, v162
	v_mov_b32_e32 v97, v120
	v_pk_mul_f32 v[94:95], v[96:97], v[94:95]
	v_mov_b32_e32 v120, v113
	v_add_f32_e32 v94, v102, v94
	v_add_f32_e32 v102, v94, v95
	v_and_b32_e32 v95, 0xffff0000, v162
	v_and_b32_e32 v94, 0xffff0000, v158
	v_pk_mul_f32 v[94:95], v[120:121], v[94:95]
	v_mov_b32_e32 v96, v114
	v_add_f32_e32 v94, v103, v94
	v_add_f32_e32 v103, v94, v95
	v_lshlrev_b32_e32 v94, 16, v157
	v_lshlrev_b32_e32 v95, 16, v161
	s_waitcnt lgkmcnt(0)
	v_mov_b32_e32 v97, v122
	v_pk_mul_f32 v[94:95], v[96:97], v[94:95]
	v_mov_b32_e32 v122, v115
	v_add_f32_e32 v94, v98, v94
	v_add_f32_e32 v98, v94, v95
	v_and_b32_e32 v95, 0xffff0000, v161
	v_and_b32_e32 v94, 0xffff0000, v157
	v_pk_mul_f32 v[94:95], v[122:123], v[94:95]
	v_mov_b32_e32 v96, v116
	v_add_f32_e32 v94, v99, v94
	v_add_f32_e32 v99, v94, v95
	v_lshlrev_b32_e32 v94, 16, v156
	v_lshlrev_b32_e32 v95, 16, v160
	v_mov_b32_e32 v97, v124
	v_pk_mul_f32 v[94:95], v[96:97], v[94:95]
	v_mul_f32_e32 v97, 0xbfb8aa3b, v101
	v_exp_f32_e32 v97, v97
	v_add_f32_e32 v94, v100, v94
	v_add_f32_e32 v96, v94, v95
	v_and_b32_e32 v95, 0xffff0000, v160
	v_and_b32_e32 v94, 0xffff0000, v156
	v_mov_b32_e32 v124, v117
	v_pk_mul_f32 v[94:95], v[124:125], v[94:95]
	v_mul_f32_e32 v100, 0xbfb8aa3b, v103
	v_add_f32_e32 v89, v89, v94
	v_add_f32_e32 v94, 1.0, v97
	v_mul_f32_e32 v97, 0xbfb8aa3b, v102
	v_add_f32_e32 v89, v89, v95
	v_mul_f32_e32 v95, 0xbfb8aa3b, v104
	v_exp_f32_e32 v97, v97
	v_exp_f32_e32 v100, v100
	v_exp_f32_e32 v95, v95
	v_rcp_f32_e32 v94, v94
	v_add_f32_e32 v97, 1.0, v97
	v_add_f32_e32 v100, 1.0, v100
	v_add_f32_e32 v95, 1.0, v95
	v_rcp_f32_e32 v97, v97
	v_rcp_f32_e32 v100, v100
	v_rcp_f32_e32 v95, v95
	v_mul_f32_e32 v94, v101, v94
	v_mul_f32_e32 v97, v102, v97
	v_mul_f32_e32 v101, 0xbfb8aa3b, v98
	v_mul_f32_e32 v102, 0xbfb8aa3b, v99
	v_mul_f32_e32 v100, v103, v100
	v_mul_f32_e32 v103, 0xbfb8aa3b, v96
	v_mul_f32_e32 v95, v104, v95
	v_exp_f32_e32 v101, v101
	v_exp_f32_e32 v102, v102
	v_exp_f32_e32 v103, v103
	v_mul_f32_e32 v104, 0xbfb8aa3b, v89
	v_exp_f32_e32 v104, v104
	v_add_f32_e32 v101, 1.0, v101
	v_add_f32_e32 v102, 1.0, v102
	v_add_f32_e32 v103, 1.0, v103
	v_rcp_f32_e32 v101, v101
	v_rcp_f32_e32 v102, v102
	v_rcp_f32_e32 v103, v103
	v_add_f32_e32 v104, 1.0, v104
	v_rcp_f32_e32 v104, v104
	s_waitcnt vmcnt(6)
	v_cndmask_b32_e32 v130, 0, v130, vcc
	s_waitcnt vmcnt(5)
	v_cndmask_b32_e64 v134, 0, v134, s[8:9]
	v_mul_f32_e32 v98, v98, v101
	v_mul_f32_e32 v99, v99, v102
	v_mul_f32_e32 v96, v96, v103
	v_mul_f32_e32 v89, v89, v104
	v_mul_f32_e32 v122, v25, v94
	v_mul_f32_e32 v123, v25, v95
	v_mul_f32_e32 v124, v25, v97
	v_mul_f32_e32 v125, v25, v100
	v_mul_f32_e32 v126, v25, v98
	v_mul_f32_e32 v127, v25, v99
	v_mul_f32_e32 v128, v25, v96
	ds_read_b128 v[94:97], v31 offset:2592
	ds_read_b128 v[98:101], v31 offset:2608
	ds_read_b128 v[102:105], v31 offset:4128
	ds_read_b128 v[106:109], v31 offset:4144
	ds_read_b128 v[110:113], v31 offset:5664
	ds_read_b128 v[114:117], v31 offset:5680
	v_lshlrev_b32_e32 v119, 16, v134
	v_lshlrev_b32_e32 v118, 16, v130
	v_mov_b32_e32 v120, v20
	s_waitcnt lgkmcnt(5)
; #define LAS __attribute__((address_space(3)))
; __device__ __forceinline__ float bflo(unsigned w) { return __uint_as_float(w << 16); }
; __device__ __forceinline__ float bfhi(unsigned w) { return __uint_as_float(w & 0xffff0000u); }
; __device__ __forceinline__ float silu_f(float x) { return x * rcp_f(1.f + exp_f(-x)); }
; __device__ __forceinline__ u32x4 pack8(const float* v) { u32x4 o; o.x = pk2(v[0], v[1]); o.y = pk2(v[2], v[3]); o.z = pk2(v[4], v[5]); o.w = pk2(v[6], v[7]); return o; }
; __device__ __forceinline__ void conv8(const u32x4 (&x)[4], const LAS float* w, float (&o)[8]) {
;     f32x4 wa[4], wb[4];
; #pragma unroll
;     for (int j = 0; j < 4; ++j) { wa[j] = *(const LAS f32x4*)(w + j * 384); wb[j] = *(const LAS f32x4*)(w + j * 384 + 4); }
; #pragma unroll
;     for (int i = 0; i < 8; ++i) o[i] = 0.f;
; #pragma unroll
;     for (int j = 0; j < 4; ++j) {
;         o[0] += wa[j].x * bflo(x[j].x); o[1] += wa[j].y * bfhi(x[j].x); o[2] += wa[j].z * bflo(x[j].y); o[3] += wa[j].w * bfhi(x[j].y);
;         o[4] += wb[j].x * bflo(x[j].z); o[5] += wb[j].y * bfhi(x[j].z); o[6] += wb[j].z * bflo(x[j].w); o[7] += wb[j].w * bfhi(x[j].w); }
; #pragma unroll
;     for (int i = 0; i < 8; ++i) o[i] = silu_f(o[i]);
; }
; __device__ __forceinline__ void prep_task(LAS unsigned char* lds, const PrepP& P, int task, int tid, int lane, int wave) {
;     ...
;         { float o[8]; conv8(xz[2][0], cw + 256, o);
; #pragma unroll
;           for (int i = 0; i < 8; ++i) x[i] = o[i] * beta;
;           conv8(xz[2][1], cw + 256 + 8, o);
; #pragma unroll
;           for (int i = 0; i < 8; ++i) x[8 + i] = o[i] * beta; }
;         *(LAS u32x4*)(Vl + lo) = pack8(x); *(LAS u32x4*)(Vl + lo + 8) = pack8(x + 8);
;         asm volatile("" ::: "memory");
;         { float o[8]; conv8(xz[1][0], cw + 128, o);
	v_mov_b32_e32 v121, v94
	v_pk_mul_f32 v[118:119], v[120:121], v[118:119]
	v_mov_b32_e32 v94, v21
	v_add_f32_e32 v20, 0, v118
	v_add_f32_e32 v120, v20, v119
	v_and_b32_e32 v119, 0xffff0000, v134
	v_and_b32_e32 v118, 0xffff0000, v130
	v_pk_mul_f32 v[20:21], v[94:95], v[118:119]
	v_cndmask_b32_e32 v131, 0, v131, vcc
	v_cndmask_b32_e64 v135, 0, v135, s[8:9]
	v_add_f32_e32 v20, 0, v20
	v_add_f32_e32 v118, v20, v21
	v_lshlrev_b32_e32 v21, 16, v135
	v_lshlrev_b32_e32 v20, 16, v131
	v_mov_b32_e32 v94, v22
	v_mov_b32_e32 v95, v96
	v_pk_mul_f32 v[20:21], v[94:95], v[20:21]
	v_mov_b32_e32 v96, v23
	v_add_f32_e32 v20, 0, v20
	v_add_f32_e32 v94, v20, v21
	v_and_b32_e32 v21, 0xffff0000, v135
	v_and_b32_e32 v20, 0xffff0000, v131
	v_pk_mul_f32 v[20:21], v[96:97], v[20:21]
	v_cndmask_b32_e32 v132, 0, v132, vcc
	v_cndmask_b32_e64 v136, 0, v136, s[8:9]
	v_add_f32_e32 v20, 0, v20
	v_add_f32_e32 v95, v20, v21
	v_lshlrev_b32_e32 v21, 16, v136
	v_lshlrev_b32_e32 v20, 16, v132
	v_mov_b32_e32 v22, v16
	s_waitcnt lgkmcnt(4)
	v_mov_b32_e32 v23, v98
	v_pk_mul_f32 v[20:21], v[22:23], v[20:21]
	v_mov_b32_e32 v98, v17
	v_add_f32_e32 v16, 0, v20
	v_add_f32_e32 v22, v16, v21
	v_and_b32_e32 v21, 0xffff0000, v136
	v_and_b32_e32 v20, 0xffff0000, v132
	v_pk_mul_f32 v[16:17], v[98:99], v[20:21]
	v_cndmask_b32_e32 v133, 0, v133, vcc
	v_cndmask_b32_e64 v137, 0, v137, s[8:9]
	v_add_f32_e32 v16, 0, v16
	v_add_f32_e32 v23, v16, v17
	v_lshlrev_b32_e32 v17, 16, v137
	v_lshlrev_b32_e32 v16, 16, v133
	v_mov_b32_e32 v20, v18
	v_mov_b32_e32 v21, v100
	v_pk_mul_f32 v[16:17], v[20:21], v[16:17]
	v_mov_b32_e32 v100, v19
	v_add_f32_e32 v16, 0, v16
	v_add_f32_e32 v20, v16, v17
	v_and_b32_e32 v17, 0xffff0000, v137
	v_and_b32_e32 v16, 0xffff0000, v133
	v_pk_mul_f32 v[16:17], v[100:101], v[16:17]
	s_waitcnt vmcnt(3)
	v_cndmask_b32_e64 v138, 0, v138, s[6:7]
	s_waitcnt vmcnt(0)
	v_cndmask_b32_e64 v142, 0, v142, s[10:11]
	v_add_f32_e32 v16, 0, v16
	v_add_f32_e32 v21, v16, v17
	v_lshlrev_b32_e32 v17, 16, v142
	v_lshlrev_b32_e32 v16, 16, v138
	s_waitcnt lgkmcnt(3)
	v_mov_b32_e32 v18, v102
	s_waitcnt lgkmcnt(1)
	v_mov_b32_e32 v19, v110
	v_pk_mul_f32 v[16:17], v[18:19], v[16:17]
	v_mov_b32_e32 v110, v103
	v_add_f32_e32 v16, v120, v16
	v_add_f32_e32 v96, v16, v17
	v_and_b32_e32 v17, 0xffff0000, v142
	v_and_b32_e32 v16, 0xffff0000, v138
	v_pk_mul_f32 v[16:17], v[110:111], v[16:17]
	v_cndmask_b32_e64 v139, 0, v139, s[6:7]
	v_cndmask_b32_e64 v143, 0, v143, s[10:11]
	v_add_f32_e32 v16, v118, v16
	v_add_f32_e32 v97, v16, v17
	v_lshlrev_b32_e32 v17, 16, v143
	v_lshlrev_b32_e32 v16, 16, v139
	v_mov_b32_e32 v18, v104
	v_mov_b32_e32 v19, v112
	v_pk_mul_f32 v[16:17], v[18:19], v[16:17]
	v_mov_b32_e32 v112, v105
	v_add_f32_e32 v16, v94, v16
	v_add_f32_e32 v94, v16, v17
	v_and_b32_e32 v17, 0xffff0000, v143
	v_and_b32_e32 v16, 0xffff0000, v139
	v_pk_mul_f32 v[16:17], v[112:113], v[16:17]
	v_cndmask_b32_e64 v140, 0, v140, s[6:7]
	v_cndmask_b32_e64 v144, 0, v144, s[10:11]
	v_add_f32_e32 v16, v95, v16
	v_add_f32_e32 v95, v16, v17
	v_lshlrev_b32_e32 v17, 16, v144
	v_lshlrev_b32_e32 v16, 16, v140
	v_mov_b32_e32 v18, v106
	s_waitcnt lgkmcnt(0)
	v_mov_b32_e32 v19, v114
	v_pk_mul_f32 v[16:17], v[18:19], v[16:17]
	v_mov_b32_e32 v114, v107
	v_add_f32_e32 v16, v22, v16
	v_add_f32_e32 v22, v16, v17
	v_and_b32_e32 v17, 0xffff0000, v144
	v_and_b32_e32 v16, 0xffff0000, v140
	v_pk_mul_f32 v[16:17], v[114:115], v[16:17]
	v_cndmask_b32_e64 v141, 0, v141, s[6:7]
	v_cndmask_b32_e64 v145, 0, v145, s[10:11]
	v_add_f32_e32 v16, v23, v16
	v_add_f32_e32 v23, v16, v17
	v_lshlrev_b32_e32 v17, 16, v145
	v_lshlrev_b32_e32 v16, 16, v141
	v_mov_b32_e32 v18, v108
	v_mov_b32_e32 v19, v116
	v_pk_mul_f32 v[16:17], v[18:19], v[16:17]
	v_mul_f32_e32 v19, 0xbfb8aa3b, v96
	v_add_f32_e32 v16, v20, v16
	v_exp_f32_e32 v19, v19
	v_add_f32_e32 v18, v16, v17
	v_and_b32_e32 v17, 0xffff0000, v145
	v_and_b32_e32 v16, 0xffff0000, v141
	v_mov_b32_e32 v116, v109
	v_pk_mul_f32 v[16:17], v[116:117], v[16:17]
	v_mul_f32_e32 v20, 0xbfb8aa3b, v94
	v_add_f32_e32 v16, v21, v16
	v_add_f32_e32 v16, v16, v17
	v_add_f32_e32 v17, 1.0, v19
	v_mul_f32_e32 v19, 0xbfb8aa3b, v97
	v_mul_f32_e32 v21, 0xbfb8aa3b, v95
	v_exp_f32_e32 v19, v19
	v_rcp_f32_e32 v17, v17
	v_exp_f32_e32 v21, v21
	v_exp_f32_e32 v20, v20
	v_add_f32_e32 v19, 1.0, v19
	v_mul_f32_e32 v17, v96, v17
	v_add_f32_e32 v21, 1.0, v21
	v_mul_f32_e32 v96, 0xbfb8aa3b, v23
	v_rcp_f32_e32 v19, v19
	v_add_f32_e32 v20, 1.0, v20
	v_rcp_f32_e32 v21, v21
	v_exp_f32_e32 v96, v96
	v_rcp_f32_e32 v20, v20
	v_mul_f32_e32 v19, v97, v19
	v_mul_f32_e32 v21, v95, v21
	v_add_f32_e32 v95, 1.0, v96
	v_mul_f32_e32 v96, 0xbfb8aa3b, v18
	v_mul_f32_e32 v97, 0xbfb8aa3b, v16
	v_mul_f32_e32 v20, v94, v20
	v_mul_f32_e32 v94, 0xbfb8aa3b, v22
	v_exp_f32_e32 v96, v96
	v_exp_f32_e32 v97, v97
	v_exp_f32_e32 v94, v94
	v_rcp_f32_e32 v95, v95
	v_add_f32_e32 v96, 1.0, v96
	v_add_f32_e32 v97, 1.0, v97
	v_add_f32_e32 v94, 1.0, v94
	v_rcp_f32_e32 v96, v96
	v_rcp_f32_e32 v97, v97
	v_rcp_f32_e32 v94, v94
	v_mul_f32_e32 v89, v25, v89
	v_mul_f32_e32 v23, v23, v95
	v_mul_f32_e32 v18, v18, v96
	v_mul_f32_e32 v16, v16, v97
	v_mul_f32_e32 v95, v25, v19
	v_cvt_pk_bf16_f32 v19, v128, v89
	v_add_lshl_u32 v89, v164, v60, 1
	v_mul_f32_e32 v22, v22, v94
	v_mul_f32_e32 v94, v25, v17
	v_mul_f32_e32 v96, v25, v18
	v_mul_f32_e32 v97, v25, v16
	v_cvt_pk_bf16_f32 v16, v122, v123
	v_cvt_pk_bf16_f32 v17, v124, v125
	v_cvt_pk_bf16_f32 v18, v126, v127
	v_add_u32_e32 v60, v58, v89
	v_mul_f32_e32 v20, v25, v20
	v_mul_f32_e32 v21, v25, v21
	v_mul_f32_e32 v22, v25, v22
	v_mul_f32_e32 v23, v25, v23
	ds_write_b128 v60, v[16:19] offset:34816
	v_cvt_pk_bf16_f32 v16, v94, v95
	v_cvt_pk_bf16_f32 v17, v20, v21
	v_cvt_pk_bf16_f32 v18, v22, v23
	v_cvt_pk_bf16_f32 v19, v96, v97
	ds_write_b128 v60, v[16:19] offset:34832
	ds_read_b128 v[94:97], v31 offset:512
	ds_read_b128 v[98:101], v31 offset:528
	ds_read_b128 v[20:23], v31 offset:544
	ds_read_b128 v[16:19], v31 offset:560
	ds_read_b128 v[102:105], v31 offset:2048
	ds_read_b128 v[106:109], v31 offset:2064
	ds_read_b128 v[110:113], v31 offset:3584
	ds_read_b128 v[114:117], v31 offset:3600
	ds_read_b128 v[118:121], v31 offset:5120
	ds_read_b128 v[122:125], v31 offset:5136
	v_lshlrev_b32_e32 v127, 16, v93
	v_lshlrev_b32_e32 v126, 16, v92
	s_waitcnt lgkmcnt(9)
; #define LAS __attribute__((address_space(3)))
; __device__ __forceinline__ float bflo(unsigned w) { return __uint_as_float(w << 16); }
; __device__ __forceinline__ float bfhi(unsigned w) { return __uint_as_float(w & 0xffff0000u); }
; __device__ __forceinline__ float silu_f(float x) { return x * rcp_f(1.f + exp_f(-x)); }
; __device__ __forceinline__ void conv8(const u32x4 (&x)[4], const LAS float* w, float (&o)[8]) {
;     f32x4 wa[4], wb[4];
; #pragma unroll
;     for (int j = 0; j < 4; ++j) { wa[j] = *(const LAS f32x4*)(w + j * 384); wb[j] = *(const LAS f32x4*)(w + j * 384 + 4); }
; #pragma unroll
;     for (int i = 0; i < 8; ++i) o[i] = 0.f;
; #pragma unroll
;     for (int j = 0; j < 4; ++j) {
;         o[0] += wa[j].x * bflo(x[j].x); o[1] += wa[j].y * bfhi(x[j].x); o[2] += wa[j].z * bflo(x[j].y); o[3] += wa[j].w * bfhi(x[j].y);
;         o[4] += wb[j].x * bflo(x[j].z); o[5] += wb[j].y * bfhi(x[j].z); o[6] += wb[j].z * bflo(x[j].w); o[7] += wb[j].w * bfhi(x[j].w); }
; #pragma unroll
;     for (int i = 0; i < 8; ++i) o[i] = silu_f(o[i]);
; }
; __device__ __forceinline__ void prep_task(LAS unsigned char* lds, const PrepP& P, int task, int tid, int lane, int wave) {
;     ...
;         { float o[8]; conv8(xz[1][0], cw + 128, o);
; #pragma unroll
;           for (int i = 0; i < 8; ++i) x[i] = o[i];
;           conv8(xz[1][1], cw + 128 + 8, o);
; #pragma unroll
;           for (int i = 0; i < 8; ++i) x[8 + i] = o[i]; }
	v_mov_b32_e32 v128, v94
	s_waitcnt lgkmcnt(5)
	v_mov_b32_e32 v129, v102
	v_and_b32_e32 v93, 0xffff0000, v93
	v_and_b32_e32 v92, 0xffff0000, v92
	v_mov_b32_e32 v102, v95
	v_pk_mul_f32 v[126:127], v[128:129], v[126:127]
	v_pk_mul_f32 v[92:93], v[102:103], v[92:93]
	v_add_f32_e32 v94, 0, v126
	v_add_f32_e32 v92, 0, v92
	v_add_f32_e32 v126, v94, v127
	v_add_f32_e32 v102, v92, v93
	v_lshlrev_b32_e32 v93, 16, v91
	v_lshlrev_b32_e32 v92, 16, v90
	v_mov_b32_e32 v94, v96
	v_mov_b32_e32 v95, v104
	v_and_b32_e32 v91, 0xffff0000, v91
	v_and_b32_e32 v90, 0xffff0000, v90
	v_mov_b32_e32 v104, v97
	v_pk_mul_f32 v[92:93], v[94:95], v[92:93]
	v_pk_mul_f32 v[90:91], v[104:105], v[90:91]
	v_add_f32_e32 v92, 0, v92
	v_add_f32_e32 v90, 0, v90
	v_add_f32_e32 v94, v92, v93
	v_add_f32_e32 v95, v90, v91
	v_lshlrev_b32_e32 v91, 16, v88
	v_lshlrev_b32_e32 v90, 16, v87
	v_mov_b32_e32 v92, v98
	s_waitcnt lgkmcnt(4)
	v_mov_b32_e32 v93, v106
	v_pk_mul_f32 v[90:91], v[92:93], v[90:91]
	v_mov_b32_e32 v106, v99
	v_add_f32_e32 v90, 0, v90
	v_add_f32_e32 v96, v90, v91
	v_and_b32_e32 v91, 0xffff0000, v88
	v_and_b32_e32 v90, 0xffff0000, v87
	v_pk_mul_f32 v[90:91], v[106:107], v[90:91]
	v_mov_b32_e32 v92, v100
	v_add_f32_e32 v87, 0, v90
	v_add_f32_e32 v88, v87, v91
	v_lshlrev_b32_e32 v91, 16, v86
	v_lshlrev_b32_e32 v90, 16, v85
	v_mov_b32_e32 v93, v108
	v_pk_mul_f32 v[90:91], v[92:93], v[90:91]
	v_mov_b32_e32 v108, v101
	v_add_f32_e32 v87, 0, v90
	v_add_f32_e32 v92, v87, v91
	v_and_b32_e32 v87, 0xffff0000, v86
	v_and_b32_e32 v86, 0xffff0000, v85
	v_pk_mul_f32 v[86:87], v[108:109], v[86:87]
	s_waitcnt lgkmcnt(3)
	v_mov_b32_e32 v90, v110
	v_add_f32_e32 v85, 0, v86
	v_add_f32_e32 v93, v85, v87
	v_lshlrev_b32_e32 v87, 16, v84
	v_lshlrev_b32_e32 v86, 16, v83
	s_waitcnt lgkmcnt(1)
	v_mov_b32_e32 v91, v118
	v_pk_mul_f32 v[86:87], v[90:91], v[86:87]
	v_mov_b32_e32 v118, v111
	v_add_f32_e32 v85, v126, v86
	v_add_f32_e32 v90, v85, v87
	v_and_b32_e32 v85, 0xffff0000, v84
	v_and_b32_e32 v84, 0xffff0000, v83
	v_pk_mul_f32 v[84:85], v[118:119], v[84:85]
	v_cndmask_b32_e64 v81, 0, v81, s[6:7]
	v_add_f32_e32 v83, v102, v84
	v_add_f32_e32 v91, v83, v85
	v_lshlrev_b32_e32 v85, 16, v82
	v_lshlrev_b32_e32 v84, 16, v81
	v_mov_b32_e32 v86, v112
	v_mov_b32_e32 v87, v120
	v_pk_mul_f32 v[84:85], v[86:87], v[84:85]
	v_mov_b32_e32 v120, v113
	v_add_f32_e32 v83, v94, v84
	v_add_f32_e32 v86, v83, v85
	v_and_b32_e32 v83, 0xffff0000, v82
	v_and_b32_e32 v82, 0xffff0000, v81
	v_pk_mul_f32 v[82:83], v[120:121], v[82:83]
	v_mov_b32_e32 v84, v114
	v_add_f32_e32 v81, v95, v82
	v_add_f32_e32 v87, v81, v83
	v_lshlrev_b32_e32 v83, 16, v80
	v_lshlrev_b32_e32 v82, 16, v79
	s_waitcnt lgkmcnt(0)
	v_mov_b32_e32 v85, v122
	v_pk_mul_f32 v[82:83], v[84:85], v[82:83]
	v_mov_b32_e32 v122, v115
	v_add_f32_e32 v81, v96, v82
	v_add_f32_e32 v84, v81, v83
	v_and_b32_e32 v81, 0xffff0000, v80
	v_and_b32_e32 v80, 0xffff0000, v79
	v_pk_mul_f32 v[80:81], v[122:123], v[80:81]
	v_mov_b32_e32 v82, v116
	v_add_f32_e32 v79, v88, v80
	v_add_f32_e32 v85, v79, v81
	v_lshlrev_b32_e32 v81, 16, v78
	v_lshlrev_b32_e32 v80, 16, v1
	v_mov_b32_e32 v83, v124
	v_pk_mul_f32 v[80:81], v[82:83], v[80:81]
	v_mov_b32_e32 v124, v117
	v_add_f32_e32 v79, v92, v80
	v_add_f32_e32 v80, v79, v81
	v_and_b32_e32 v79, 0xffff0000, v78
	v_and_b32_e32 v78, 0xffff0000, v1
	v_pk_mul_f32 v[78:79], v[124:125], v[78:79]
	v_mul_f32_e32 v1, 0xbfb8aa3b, v90
	v_add_f32_e32 v78, v93, v78
	v_add_f32_e32 v78, v78, v79
	v_mul_f32_e32 v79, 0xbfb8aa3b, v91
	v_mul_f32_e32 v81, 0xbfb8aa3b, v86
	v_exp_f32_e32 v1, v1
	v_exp_f32_e32 v79, v79
	v_exp_f32_e32 v81, v81
	v_mul_f32_e32 v82, 0xbfb8aa3b, v87
	v_add_f32_e32 v1, 1.0, v1
	v_add_f32_e32 v79, 1.0, v79
	v_add_f32_e32 v81, 1.0, v81
	v_rcp_f32_e32 v1, v1
	v_rcp_f32_e32 v79, v79
	v_rcp_f32_e32 v81, v81
	v_exp_f32_e32 v82, v82
	v_mul_f32_e32 v88, v90, v1
	v_mul_f32_e32 v108, v91, v79
	v_mul_f32_e32 v109, v86, v81
	v_add_f32_e32 v1, 1.0, v82
	v_mul_f32_e32 v79, 0xbfb8aa3b, v84
	v_mul_f32_e32 v81, 0xbfb8aa3b, v85
	v_rcp_f32_e32 v1, v1
	v_exp_f32_e32 v79, v79
	v_exp_f32_e32 v81, v81
	v_mul_f32_e32 v82, 0xbfb8aa3b, v78
	v_mul_f32_e32 v110, v87, v1
	v_add_f32_e32 v1, 1.0, v79
	v_add_f32_e32 v79, 1.0, v81
	v_mul_f32_e32 v81, 0xbfb8aa3b, v80
	v_exp_f32_e32 v81, v81
	v_exp_f32_e32 v82, v82
	v_rcp_f32_e32 v1, v1
	v_rcp_f32_e32 v79, v79
	v_add_f32_e32 v81, 1.0, v81
	v_add_f32_e32 v82, 1.0, v82
	v_rcp_f32_e32 v81, v81
	v_rcp_f32_e32 v82, v82
	v_mul_f32_e32 v111, v84, v1
	v_mul_f32_e32 v112, v85, v79
	v_mul_f32_e32 v1, v80, v81
	v_mul_f32_e32 v113, v78, v82
	ds_read_b128 v[78:81], v31 offset:2080
	ds_read_b128 v[82:85], v31 offset:2096
	ds_read_b128 v[90:93], v31 offset:3616
	ds_read_b128 v[94:97], v31 offset:3632
	ds_read_b128 v[98:101], v31 offset:5152
	ds_read_b128 v[102:105], v31 offset:5168
	v_lshlrev_b32_e32 v87, 16, v77
	v_lshlrev_b32_e32 v86, 16, v76
	v_mov_b32_e32 v106, v20
	s_waitcnt lgkmcnt(5)
	v_mov_b32_e32 v107, v78
	v_pk_mul_f32 v[86:87], v[106:107], v[86:87]
	v_and_b32_e32 v77, 0xffff0000, v77
	v_add_f32_e32 v20, 0, v86
	v_and_b32_e32 v76, 0xffff0000, v76
	v_mov_b32_e32 v78, v21
	v_add_f32_e32 v86, v20, v87
	v_pk_mul_f32 v[20:21], v[78:79], v[76:77]
	v_mov_b32_e32 v76, v22
	v_add_f32_e32 v20, 0, v20
	v_add_f32_e32 v78, v20, v21
	v_lshlrev_b32_e32 v21, 16, v75
	v_lshlrev_b32_e32 v20, 16, v74
	v_mov_b32_e32 v77, v80
	v_and_b32_e32 v75, 0xffff0000, v75
	v_and_b32_e32 v74, 0xffff0000, v74
	v_mov_b32_e32 v80, v23
	v_pk_mul_f32 v[20:21], v[76:77], v[20:21]
	v_pk_mul_f32 v[22:23], v[80:81], v[74:75]
	v_lshlrev_b32_e32 v75, 16, v73
	v_lshlrev_b32_e32 v74, 16, v72
	s_waitcnt lgkmcnt(3)
	v_mov_b32_e32 v76, v90
	s_waitcnt lgkmcnt(1)
; __device__ __forceinline__ float rsq_f(float x) { return __builtin_amdgcn_rsqf(x); }
; __device__ __forceinline__ float exp_f(float x) { return __builtin_amdgcn_exp2f(x * 1.4426950408889634f); }
; __device__ __forceinline__ void prep_task(LAS unsigned char* lds, const PrepP& P, int task, int tid, int lane, int wave) {
;     ...
;           conv8(xz[1][1], cw + 128 + 8, o);
; #pragma unroll
;           for (int i = 0; i < 8; ++i) x[8 + i] = o[i]; }
;         { float sk = 0.f;
; #pragma unroll
;           for (int i = 0; i < 16; ++i) sk += x[i] * x[i];
;           sk += __shfl_xor(sk, 1); sk += __shfl_xor(sk, 2); sk += __shfl_xor(sk, 4);
;           const float rk = rsq_f(sk + EPS);
	v_mov_b32_e32 v77, v98
	v_and_b32_e32 v73, 0xffff0000, v73
	v_and_b32_e32 v72, 0xffff0000, v72
	v_mov_b32_e32 v98, v91
	v_pk_mul_f32 v[74:75], v[76:77], v[74:75]
	v_pk_mul_f32 v[72:73], v[98:99], v[72:73]
	v_add_f32_e32 v74, v86, v74
	v_add_f32_e32 v72, v78, v72
	v_add_f32_e32 v76, v74, v75
	v_add_f32_e32 v77, v72, v73
	v_lshlrev_b32_e32 v73, 16, v71
	v_lshlrev_b32_e32 v72, 16, v70
	v_mov_b32_e32 v74, v92
	v_mov_b32_e32 v75, v100
	v_pk_mul_f32 v[72:73], v[74:75], v[72:73]
	v_mul_f32_e32 v74, 0xbfb8aa3b, v76
	v_mul_f32_e32 v75, 0xbfb8aa3b, v77
	v_exp_f32_e32 v74, v74
	v_exp_f32_e32 v75, v75
	v_and_b32_e32 v71, 0xffff0000, v71
	v_and_b32_e32 v70, 0xffff0000, v70
	v_add_f32_e32 v74, 1.0, v74
	v_add_f32_e32 v75, 1.0, v75
	v_rcp_f32_e32 v74, v74
	v_rcp_f32_e32 v75, v75
	v_mov_b32_e32 v100, v93
	v_pk_mul_f32 v[70:71], v[100:101], v[70:71]
	v_mul_f32_e32 v76, v76, v74
	v_mul_f32_e32 v77, v77, v75
	v_mov_b32_e32 v74, v22
	v_mov_b32_e32 v75, v20
	v_pk_add_f32 v[74:75], v[74:75], 0 op_sel_hi:[1,0]
	v_mov_b32_e32 v20, v23
	v_pk_add_f32 v[20:21], v[74:75], v[20:21]
	v_mov_b32_e32 v22, v70
	v_mov_b32_e32 v23, v72
	v_pk_add_f32 v[20:21], v[20:21], v[22:23]
	v_mov_b32_e32 v72, v71
	v_pk_add_f32 v[20:21], v[20:21], v[72:73]
	v_mul_f32_e32 v78, v108, v108
	v_mul_f32_e32 v22, 0xbfb8aa3b, v21
	v_exp_f32_e32 v22, v22
	v_mul_f32_e32 v23, 0xbfb8aa3b, v20
	v_exp_f32_e32 v70, v23
	v_fmac_f32_e32 v78, v88, v88
	v_add_f32_e32 v22, 1.0, v22
	v_rcp_f32_e32 v23, v22
	v_add_f32_e32 v22, 1.0, v70
	v_and_b32_e32 v71, 0xffff0000, v69
	v_lshlrev_b32_e32 v70, 16, v69
	v_fmac_f32_e32 v78, v109, v109
	v_pk_fma_f32 v[16:17], v[16:17], v[70:71], 0 op_sel_hi:[1,1,0]
	v_and_b32_e32 v69, 0xffff0000, v68
	v_lshlrev_b32_e32 v68, 16, v68
	v_fmac_f32_e32 v78, v110, v110
	v_pk_fma_f32 v[16:17], v[82:83], v[68:69], v[16:17]
	v_and_b32_e32 v69, 0xffff0000, v67
	v_lshlrev_b32_e32 v68, 16, v67
	v_fmac_f32_e32 v78, v111, v111
	v_rcp_f32_e32 v22, v22
	v_pk_fma_f32 v[16:17], v[94:95], v[68:69], v[16:17]
	v_and_b32_e32 v67, 0xffff0000, v66
	v_lshlrev_b32_e32 v66, 16, v66
	v_fmac_f32_e32 v78, v112, v112
	s_waitcnt lgkmcnt(0)
	v_pk_fma_f32 v[16:17], v[102:103], v[66:67], v[16:17]
	v_fmac_f32_e32 v78, v1, v1
	v_mul_f32_e32 v66, 0xbfb8aa3b, v16
	v_mul_f32_e32 v67, 0xbfb8aa3b, v17
	v_fmac_f32_e32 v78, v113, v113
	v_exp_f32_e32 v66, v66
	v_exp_f32_e32 v67, v67
	v_fmac_f32_e32 v78, v76, v76
	v_pk_mul_f32 v[20:21], v[20:21], v[22:23]
	v_fmac_f32_e32 v78, v77, v77
	v_pk_mul_f32 v[22:23], v[20:21], v[20:21]
	v_cndmask_b32_e64 v95, 0, v13, s[8:9]
	v_add_f32_e32 v23, v23, v78
	v_add_f32_e32 v68, v22, v23
	v_add_f32_e32 v22, 1.0, v66
	v_add_f32_e32 v23, 1.0, v67
	v_and_b32_e32 v67, 0xffff0000, v65
	v_lshlrev_b32_e32 v66, 16, v65
	v_pk_fma_f32 v[18:19], v[18:19], v[66:67], 0 op_sel_hi:[1,1,0]
	v_and_b32_e32 v65, 0xffff0000, v64
	v_lshlrev_b32_e32 v64, 16, v64
	v_pk_fma_f32 v[18:19], v[84:85], v[64:65], v[18:19]
	v_and_b32_e32 v65, 0xffff0000, v3
	v_lshlrev_b32_e32 v64, 16, v3
	v_pk_fma_f32 v[18:19], v[96:97], v[64:65], v[18:19]
	v_and_b32_e32 v3, 0xffff0000, v2
	v_lshlrev_b32_e32 v2, 16, v2
	v_pk_fma_f32 v[2:3], v[104:105], v[2:3], v[18:19]
	v_rcp_f32_e32 v22, v22
	v_mul_f32_e32 v18, 0xbfb8aa3b, v2
	v_exp_f32_e32 v64, v18
	v_mul_f32_e32 v18, 0xbfb8aa3b, v3
	v_rcp_f32_e32 v23, v23
	v_exp_f32_e32 v65, v18
	v_xor_b32_e32 v13, 2, v192
	v_cndmask_b32_e32 v94, 0, v0, vcc
	v_pk_mul_f32 v[18:19], v[16:17], v[22:23]
	v_add_f32_e32 v16, 1.0, v64
	v_add_f32_e32 v17, 1.0, v65
	v_rcp_f32_e32 v16, v16
	v_rcp_f32_e32 v17, v17
	v_pk_mul_f32 v[22:23], v[18:19], v[18:19]
	v_cndmask_b32_e64 v98, 0, v9, s[6:7]
	v_add_f32_e32 v22, v22, v68
	v_pk_mul_f32 v[2:3], v[2:3], v[16:17]
	v_add_f32_e32 v22, v23, v22
	v_pk_mul_f32 v[16:17], v[2:3], v[2:3]
	v_xor_b32_e32 v9, 4, v192
	v_add_f32_e32 v16, v16, v22
	v_and_b32_e32 v22, 64, v192
	v_add_f32_e32 v17, v17, v16
	v_xor_b32_e32 v16, 1, v192
	v_add_u32_e32 v22, 64, v22
	v_cmp_lt_i32_e64 s[14:15], v16, v22
	v_cmp_lt_i32_e32 vcc, v13, v22
	v_cndmask_b32_e64 v97, 0, v10, s[6:7]
	v_cndmask_b32_e64 v16, v192, v16, s[14:15]
	v_lshlrev_b32_e32 v16, 2, v16
	ds_bpermute_b32 v23, v16, v17
	v_cndmask_b32_e32 v13, v192, v13, vcc
	v_lshlrev_b32_e32 v13, 2, v13
	v_cmp_lt_i32_e32 vcc, v9, v22
	v_exp_f32_e32 v22, v62
	s_waitcnt lgkmcnt(0)
	v_add_f32_e32 v0, v17, v23
	ds_bpermute_b32 v17, v13, v0
	v_cndmask_b32_e32 v9, v192, v9, vcc
	v_lshlrev_b32_e32 v10, 2, v9
	v_cndmask_b32_e64 v96, 0, v12, s[8:9]
	v_cndmask_b32_e64 v12, 0, v7, s[10:11]
	s_waitcnt lgkmcnt(0)
	v_add_f32_e32 v0, v0, v17
	ds_bpermute_b32 v9, v10, v0
	v_cndmask_b32_e64 v17, 0, v8, s[6:7]
	v_exp_f32_e32 v8, v61
	v_cndmask_b32_e64 v99, 0, v6, s[10:11]
	v_cndmask_b32_e64 v100, 0, v5, s[10:11]
	s_waitcnt lgkmcnt(0)
; #define LAS __attribute__((address_space(3)))
; __device__ __forceinline__ float rsq_f(float x) { return __builtin_amdgcn_rsqf(x); }
; __device__ __forceinline__ u32x4 pack8(const float* v) { u32x4 o; o.x = pk2(v[0], v[1]); o.y = pk2(v[2], v[3]); o.z = pk2(v[4], v[5]); o.w = pk2(v[6], v[7]); return o; }
; __device__ __forceinline__ void prep_task(LAS unsigned char* lds, const PrepP& P, int task, int tid, int lane, int wave) {
;     ...
;           const float rk = rsq_f(sk + EPS);
; #pragma unroll
;           for (int i = 0; i < 16; ++i) x[i] *= rk; }
;         *(LAS u32x4*)(Kl + lo) = pack8(x); *(LAS u32x4*)(Kl + lo + 8) = pack8(x + 8);
; #pragma unroll
;         for (int i = 0; i < 16; ++i) y[i] = x[i] * (beta * eg);
;         *(LAS u32x4*)(KBl + lo) = pack8(y); *(LAS u32x4*)(KBl + lo + 8) = pack8(y + 8);
; #pragma unroll
;         for (int i = 0; i < 16; ++i) y[i] = x[i] * et;
;         *(LAS u32x4*)(KTl + lo) = pack8(y); *(LAS u32x4*)(KTl + lo + 8) = pack8(y + 8);
;         asm volatile("" ::: "memory");
;         { float o[8]; conv8(xz[0][0], cw, o);
; #pragma unroll
;           for (int i = 0; i < 8; ++i) x[i] = o[i];
;           conv8(xz[0][1], cw + 8, o);
; #pragma unroll
;           for (int i = 0; i < 8; ++i) x[8 + i] = o[i]; }
	v_add_f32_e32 v0, v0, v9
	v_add_f32_e32 v0, 0x358637bd, v0
	v_rsq_f32_e32 v9, v0
	v_mov_b32_e32 v0, v25
	v_cndmask_b32_e64 v101, 0, v4, s[10:11]
	v_cndmask_b32_e64 v14, 0, v14, s[8:9]
	v_mul_f32_e32 v23, v88, v9
	v_mul_f32_e32 v61, v108, v9
	v_mul_f32_e32 v62, v109, v9
	v_mul_f32_e32 v64, v110, v9
	v_mul_f32_e32 v70, v2, v9
	v_mul_f32_e32 v71, v3, v9
	v_cvt_pk_bf16_f32 v2, v23, v61
	v_cvt_pk_bf16_f32 v3, v62, v64
	v_mul_f32_e32 v65, v111, v9
	v_mul_f32_e32 v66, v112, v9
	v_mul_f32_e32 v67, v113, v9
	v_mul_f32_e32 v68, v76, v9
	v_mul_f32_e32 v69, v77, v9
	v_mul_f32_e32 v21, v21, v9
	v_mul_f32_e32 v20, v20, v9
	v_mul_f32_e32 v18, v18, v9
	v_mul_f32_e32 v19, v19, v9
	v_cvt_pk_bf16_f32 v4, v65, v66
	v_pk_mul_f32 v[6:7], v[0:1], v[8:9]
	v_cvt_pk_bf16_f32 v0, v68, v69
	v_cvt_pk_bf16_f32 v1, v21, v20
	v_cndmask_b32_e64 v15, 0, v15, s[8:9]
	v_cvt_pk_bf16_f32 v5, v7, v67
	ds_write_b128 v60, v[2:5]
	v_cvt_pk_bf16_f32 v2, v18, v19
	v_cvt_pk_bf16_f32 v3, v70, v71
	ds_write_b128 v60, v[0:3] offset:16
	v_mul_f32_e32 v0, v6, v23
	v_mul_f32_e32 v1, v6, v61
	v_mul_f32_e32 v2, v6, v62
	v_mul_f32_e32 v3, v6, v64
	v_mul_f32_e32 v4, v6, v65
	v_mul_f32_e32 v5, v6, v66
	v_mul_f32_e32 v9, v6, v7
	v_mul_f32_e32 v25, v6, v67
	v_cvt_pk_bf16_f32 v0, v0, v1
	v_cvt_pk_bf16_f32 v1, v2, v3
	v_cvt_pk_bf16_f32 v2, v4, v5
	v_cvt_pk_bf16_f32 v3, v9, v25
	v_mul_f32_e32 v72, v6, v68
	v_mul_f32_e32 v73, v6, v69
	v_mul_f32_e32 v74, v6, v21
	v_mul_f32_e32 v75, v6, v20
	v_mul_f32_e32 v76, v6, v18
	v_mul_f32_e32 v77, v6, v19
	v_mul_f32_e32 v78, v6, v70
	v_mul_f32_e32 v6, v6, v71
	ds_write_b128 v60, v[0:3] offset:52224
	v_cvt_pk_bf16_f32 v0, v72, v73
	v_cvt_pk_bf16_f32 v1, v74, v75
	v_cvt_pk_bf16_f32 v2, v76, v77
	v_cvt_pk_bf16_f32 v3, v78, v6
	ds_write_b128 v60, v[0:3] offset:52240
	v_mul_f32_e32 v0, v22, v23
	v_mul_f32_e32 v1, v22, v61
	v_mul_f32_e32 v2, v22, v62
	v_mul_f32_e32 v3, v22, v64
	v_mul_f32_e32 v4, v22, v65
	v_mul_f32_e32 v5, v22, v66
	v_mul_f32_e32 v6, v22, v7
	v_mul_f32_e32 v7, v22, v67
	v_cvt_pk_bf16_f32 v0, v0, v1
	v_cvt_pk_bf16_f32 v1, v2, v3
	v_cvt_pk_bf16_f32 v2, v4, v5
	v_cvt_pk_bf16_f32 v3, v6, v7
	v_add_u32_e32 v4, v57, v89
	v_mul_f32_e32 v9, v22, v68
	v_mul_f32_e32 v23, v22, v69
	v_mul_f32_e32 v21, v22, v21
	v_mul_f32_e32 v20, v22, v20
	v_mul_f32_e32 v18, v22, v18
	v_mul_f32_e32 v19, v22, v19
	v_mul_f32_e32 v25, v22, v70
	v_mul_f32_e32 v22, v22, v71
	ds_write_b128 v4, v[0:3]
	v_cvt_pk_bf16_f32 v0, v9, v23
	v_cvt_pk_bf16_f32 v1, v21, v20
	v_cvt_pk_bf16_f32 v2, v18, v19
	v_cvt_pk_bf16_f32 v3, v25, v22
	ds_write_b128 v4, v[0:3] offset:16
	ds_read_b128 v[18:21], v31
	ds_read_b128 v[64:67], v31 offset:16
	ds_read_b128 v[4:7], v31 offset:32
	ds_read_b128 v[0:3], v31 offset:48
	ds_read_b128 v[68:71], v31 offset:1536
	ds_read_b128 v[72:75], v31 offset:1552
	ds_read_b128 v[76:79], v31 offset:3072
	ds_read_b128 v[80:83], v31 offset:3088
	ds_read_b128 v[84:87], v31 offset:4608
	ds_read_b128 v[88:91], v31 offset:4624
	v_lshlrev_b32_e32 v23, 16, v59
	v_lshlrev_b32_e32 v22, 16, v53
	s_waitcnt lgkmcnt(9)
	v_mov_b32_e32 v92, v18
	s_waitcnt lgkmcnt(5)
	v_mov_b32_e32 v93, v68
	v_pk_mul_f32 v[22:23], v[92:93], v[22:23]
	v_mov_b32_e32 v68, v19
	v_add_f32_e32 v9, 0, v22
	v_add_f32_e32 v9, v9, v23
	v_and_b32_e32 v23, 0xffff0000, v59
	v_and_b32_e32 v22, 0xffff0000, v53
	v_pk_mul_f32 v[18:19], v[68:69], v[22:23]
	v_mov_b32_e32 v22, v20
	v_add_f32_e32 v18, 0, v18
	v_add_f32_e32 v25, v18, v19
	v_lshlrev_b32_e32 v19, 16, v52
	v_lshlrev_b32_e32 v18, 16, v51
	v_mov_b32_e32 v23, v70
	v_pk_mul_f32 v[18:19], v[22:23], v[18:19]
	v_mov_b32_e32 v70, v21
	v_add_f32_e32 v18, 0, v18
	v_add_f32_e32 v22, v18, v19
	v_and_b32_e32 v19, 0xffff0000, v52
	v_and_b32_e32 v18, 0xffff0000, v51
	v_pk_mul_f32 v[18:19], v[70:71], v[18:19]
	v_mov_b32_e32 v20, v64
	v_add_f32_e32 v18, 0, v18
	v_add_f32_e32 v23, v18, v19
	v_lshlrev_b32_e32 v19, 16, v50
	v_lshlrev_b32_e32 v18, 16, v49
	s_waitcnt lgkmcnt(4)
	v_mov_b32_e32 v21, v72
	v_pk_mul_f32 v[18:19], v[20:21], v[18:19]
	v_mov_b32_e32 v72, v65
	v_add_f32_e32 v18, 0, v18
	v_add_f32_e32 v51, v18, v19
	v_and_b32_e32 v19, 0xffff0000, v50
	v_and_b32_e32 v18, 0xffff0000, v49
	v_pk_mul_f32 v[18:19], v[72:73], v[18:19]
	v_mov_b32_e32 v20, v66
	v_add_f32_e32 v18, 0, v18
	v_add_f32_e32 v49, v18, v19
	v_lshlrev_b32_e32 v19, 16, v39
	v_lshlrev_b32_e32 v18, 16, v38
	v_mov_b32_e32 v21, v74
	v_pk_mul_f32 v[18:19], v[20:21], v[18:19]
	v_mov_b32_e32 v74, v67
	v_add_f32_e32 v18, 0, v18
	v_add_f32_e32 v50, v18, v19
	v_and_b32_e32 v19, 0xffff0000, v39
	v_and_b32_e32 v18, 0xffff0000, v38
	v_pk_mul_f32 v[18:19], v[74:75], v[18:19]
	s_waitcnt lgkmcnt(3)
	v_mov_b32_e32 v20, v76
	v_add_f32_e32 v18, 0, v18
	v_add_f32_e32 v38, v18, v19
	v_lshlrev_b32_e32 v18, 16, v37
	v_lshlrev_b32_e32 v19, 16, v36
	s_waitcnt lgkmcnt(1)
	v_mov_b32_e32 v21, v84
	v_pk_mul_f32 v[18:19], v[20:21], v[18:19]
	v_mov_b32_e32 v84, v77
	v_add_f32_e32 v9, v9, v18
	v_add_f32_e32 v9, v9, v19
	v_and_b32_e32 v19, 0xffff0000, v36
	v_and_b32_e32 v18, 0xffff0000, v37
	v_pk_mul_f32 v[18:19], v[84:85], v[18:19]
	v_mov_b32_e32 v20, v78
	v_add_f32_e32 v18, v25, v18
	v_add_f32_e32 v25, v18, v19
	v_lshlrev_b32_e32 v18, 16, v35
	v_lshlrev_b32_e32 v19, 16, v34
	v_mov_b32_e32 v21, v86
	v_pk_mul_f32 v[18:19], v[20:21], v[18:19]
	v_mov_b32_e32 v86, v79
	v_add_f32_e32 v18, v22, v18
	v_add_f32_e32 v22, v18, v19
	v_and_b32_e32 v19, 0xffff0000, v34
	v_and_b32_e32 v18, 0xffff0000, v35
	v_pk_mul_f32 v[18:19], v[86:87], v[18:19]
	v_mov_b32_e32 v20, v80
	v_add_f32_e32 v18, v23, v18
	v_add_f32_e32 v23, v18, v19
	v_lshlrev_b32_e32 v18, 16, v33
	v_lshlrev_b32_e32 v19, 16, v32
	s_waitcnt lgkmcnt(0)
; #define LAS __attribute__((address_space(3)))
; __device__ __forceinline__ float bflo(unsigned w) { return __uint_as_float(w << 16); }
; __device__ __forceinline__ float bfhi(unsigned w) { return __uint_as_float(w & 0xffff0000u); }
; __device__ __forceinline__ float silu_f(float x) { return x * rcp_f(1.f + exp_f(-x)); }
; __device__ __forceinline__ void conv8(const u32x4 (&x)[4], const LAS float* w, float (&o)[8]) {
;     f32x4 wa[4], wb[4];
; #pragma unroll
;     for (int j = 0; j < 4; ++j) { wa[j] = *(const LAS f32x4*)(w + j * 384); wb[j] = *(const LAS f32x4*)(w + j * 384 + 4); }
; #pragma unroll
;     for (int i = 0; i < 8; ++i) o[i] = 0.f;
; #pragma unroll
;     for (int j = 0; j < 4; ++j) {
;         o[0] += wa[j].x * bflo(x[j].x); o[1] += wa[j].y * bfhi(x[j].x); o[2] += wa[j].z * bflo(x[j].y); o[3] += wa[j].w * bfhi(x[j].y);
;         o[4] += wb[j].x * bflo(x[j].z); o[5] += wb[j].y * bfhi(x[j].z); o[6] += wb[j].z * bflo(x[j].w); o[7] += wb[j].w * bfhi(x[j].w); }
; #pragma unroll
;     for (int i = 0; i < 8; ++i) o[i] = silu_f(o[i]);
; }
; __device__ __forceinline__ void prep_task(LAS unsigned char* lds, const PrepP& P, int task, int tid, int lane, int wave) {
;     ...
;         { float o[8]; conv8(xz[0][0], cw, o);
; #pragma unroll
;           for (int i = 0; i < 8; ++i) x[i] = o[i];
;           conv8(xz[0][1], cw + 8, o);
; #pragma unroll
;           for (int i = 0; i < 8; ++i) x[8 + i] = o[i]; }
	v_mov_b32_e32 v21, v88
	v_pk_mul_f32 v[18:19], v[20:21], v[18:19]
	v_mov_b32_e32 v88, v81
	v_add_f32_e32 v18, v51, v18
	v_add_f32_e32 v34, v18, v19
	v_and_b32_e32 v19, 0xffff0000, v32
	v_and_b32_e32 v18, 0xffff0000, v33
	v_pk_mul_f32 v[18:19], v[88:89], v[18:19]
	v_mov_b32_e32 v20, v82
	v_add_f32_e32 v18, v49, v18
	v_add_f32_e32 v32, v18, v19
	v_lshlrev_b32_e32 v18, 16, v30
	v_lshlrev_b32_e32 v19, 16, v29
	v_mov_b32_e32 v21, v90
	v_pk_mul_f32 v[18:19], v[20:21], v[18:19]
	v_mul_f32_e32 v21, 0xbfb8aa3b, v9
	v_add_f32_e32 v18, v50, v18
	v_exp_f32_e32 v21, v21
	v_add_f32_e32 v20, v18, v19
	v_and_b32_e32 v19, 0xffff0000, v29
	v_and_b32_e32 v18, 0xffff0000, v30
	v_mov_b32_e32 v90, v83
	v_pk_mul_f32 v[18:19], v[90:91], v[18:19]
	v_mul_f32_e32 v29, 0xbfb8aa3b, v22
	v_add_f32_e32 v18, v38, v18
	v_add_f32_e32 v18, v18, v19
	v_add_f32_e32 v19, 1.0, v21
	v_mul_f32_e32 v21, 0xbfb8aa3b, v25
	v_exp_f32_e32 v21, v21
	v_exp_f32_e32 v29, v29
	v_mul_f32_e32 v30, 0xbfb8aa3b, v23
	v_rcp_f32_e32 v19, v19
	v_add_f32_e32 v21, 1.0, v21
	v_add_f32_e32 v29, 1.0, v29
	v_rcp_f32_e32 v21, v21
	v_rcp_f32_e32 v29, v29
	v_exp_f32_e32 v30, v30
	v_mul_f32_e32 v9, v9, v19
	v_mul_f32_e32 v25, v25, v21
	v_mul_f32_e32 v29, v22, v29
	v_add_f32_e32 v19, 1.0, v30
	v_mul_f32_e32 v21, 0xbfb8aa3b, v34
	v_mul_f32_e32 v22, 0xbfb8aa3b, v32
	v_rcp_f32_e32 v19, v19
	v_exp_f32_e32 v21, v21
	v_exp_f32_e32 v22, v22
	v_mov_b32_e32 v30, v4
	v_mul_f32_e32 v49, v23, v19
	v_add_f32_e32 v19, 1.0, v21
	v_add_f32_e32 v21, 1.0, v22
	v_mul_f32_e32 v22, 0xbfb8aa3b, v20
	v_mul_f32_e32 v23, 0xbfb8aa3b, v18
	v_exp_f32_e32 v22, v22
	v_exp_f32_e32 v23, v23
	v_rcp_f32_e32 v19, v19
	v_rcp_f32_e32 v21, v21
	v_add_f32_e32 v22, 1.0, v22
	v_add_f32_e32 v23, 1.0, v23
	v_rcp_f32_e32 v22, v22
	v_rcp_f32_e32 v23, v23
	v_mul_f32_e32 v61, v34, v19
	v_mul_f32_e32 v72, v32, v21
	v_mul_f32_e32 v73, v20, v22
	v_mul_f32_e32 v74, v18, v23
	ds_read_b128 v[18:21], v31 offset:1568
	ds_read_b128 v[32:35], v31 offset:1584
	ds_read_b128 v[36:39], v31 offset:3104
	ds_read_b128 v[50:53], v31 offset:3120
	ds_read_b128 v[64:67], v31 offset:4640
	ds_read_b128 v[68:71], v31 offset:4656
	v_lshlrev_b32_e32 v23, 16, v96
	v_lshlrev_b32_e32 v22, 16, v94
	s_waitcnt lgkmcnt(5)
	v_mov_b32_e32 v31, v18
	v_pk_mul_f32 v[22:23], v[30:31], v[22:23]
	v_mov_b32_e32 v18, v5
	v_add_f32_e32 v4, 0, v22
	v_add_f32_e32 v30, v4, v23
	v_and_b32_e32 v23, 0xffff0000, v96
	v_and_b32_e32 v22, 0xffff0000, v94
	v_pk_mul_f32 v[4:5], v[18:19], v[22:23]
	v_mov_b32_e32 v18, v6
	v_add_f32_e32 v4, 0, v4
	v_add_f32_e32 v22, v4, v5
	v_lshlrev_b32_e32 v5, 16, v95
	v_lshlrev_b32_e32 v4, 16, v28
	v_mov_b32_e32 v19, v20
	v_pk_mul_f32 v[4:5], v[18:19], v[4:5]
	v_mov_b32_e32 v20, v7
	v_add_f32_e32 v4, 0, v4
	v_add_f32_e32 v18, v4, v5
	v_and_b32_e32 v5, 0xffff0000, v95
	v_and_b32_e32 v4, 0xffff0000, v28
	v_pk_mul_f32 v[4:5], v[20:21], v[4:5]
	s_waitcnt lgkmcnt(3)
	v_mov_b32_e32 v6, v36
	v_add_f32_e32 v4, 0, v4
	v_add_f32_e32 v19, v4, v5
	v_lshlrev_b32_e32 v5, 16, v101
	v_lshlrev_b32_e32 v4, 16, v17
	s_waitcnt lgkmcnt(1)
	v_mov_b32_e32 v7, v64
	v_pk_mul_f32 v[4:5], v[6:7], v[4:5]
	v_mov_b32_e32 v64, v37
	v_add_f32_e32 v4, v30, v4
	v_add_f32_e32 v20, v4, v5
	v_and_b32_e32 v5, 0xffff0000, v101
	v_and_b32_e32 v4, 0xffff0000, v17
	v_pk_mul_f32 v[4:5], v[64:65], v[4:5]
	v_mov_b32_e32 v6, v38
	v_add_f32_e32 v4, v22, v4
	v_add_f32_e32 v17, v4, v5
	v_lshlrev_b32_e32 v5, 16, v100
	v_lshlrev_b32_e32 v4, 16, v98
	v_mov_b32_e32 v7, v66
	v_pk_mul_f32 v[4:5], v[6:7], v[4:5]
	v_mov_b32_e32 v66, v39
	v_add_f32_e32 v4, v18, v4
	v_add_f32_e32 v6, v4, v5
	v_and_b32_e32 v5, 0xffff0000, v100
	v_and_b32_e32 v4, 0xffff0000, v98
	v_pk_mul_f32 v[4:5], v[66:67], v[4:5]
	v_mul_f32_e32 v7, 0xbfb8aa3b, v20
	v_add_f32_e32 v4, v19, v4
	v_add_f32_e32 v4, v4, v5
	v_mul_f32_e32 v18, 0xbfb8aa3b, v17
	v_mul_f32_e32 v19, 0xbfb8aa3b, v4
	v_exp_f32_e32 v7, v7
	v_exp_f32_e32 v18, v18
	v_exp_f32_e32 v19, v19
	v_cndmask_b32_e64 v11, 0, v11, s[6:7]
	v_add_f32_e32 v5, 1.0, v7
	v_add_f32_e32 v7, 1.0, v18
	v_mul_f32_e32 v18, 0xbfb8aa3b, v6
	v_add_f32_e32 v19, 1.0, v19
	v_rcp_f32_e32 v5, v5
	v_exp_f32_e32 v18, v18
	v_rcp_f32_e32 v19, v19
	v_rcp_f32_e32 v7, v7
	v_mul_f32_e32 v20, v20, v5
	v_add_f32_e32 v18, 1.0, v18
	v_mul_f32_e32 v19, v4, v19
	v_and_b32_e32 v5, 0xffff0000, v27
	v_lshlrev_b32_e32 v4, 16, v27
	v_rcp_f32_e32 v18, v18
	v_pk_fma_f32 v[0:1], v[0:1], v[4:5], 0 op_sel_hi:[1,1,0]
	v_and_b32_e32 v5, 0xffff0000, v14
	v_lshlrev_b32_e32 v4, 16, v14
	v_pk_fma_f32 v[0:1], v[32:33], v[4:5], v[0:1]
	v_and_b32_e32 v5, 0xffff0000, v97
	v_lshlrev_b32_e32 v4, 16, v97
	v_pk_fma_f32 v[0:1], v[50:51], v[4:5], v[0:1]
	v_and_b32_e32 v5, 0xffff0000, v99
	v_lshlrev_b32_e32 v4, 16, v99
	s_waitcnt lgkmcnt(0)
; #define LAS __attribute__((address_space(3)))
; __device__ __forceinline__ float rsq_f(float x) { return __builtin_amdgcn_rsqf(x); }
; #define LBAR() do { asm volatile("s_waitcnt lgkmcnt(0)" ::: "memory"); __builtin_amdgcn_s_barrier(); asm volatile("" ::: "memory"); } while (0)
; __device__ __forceinline__ u32x4 pack8(const float* v) { u32x4 o; o.x = pk2(v[0], v[1]); o.y = pk2(v[2], v[3]); o.z = pk2(v[4], v[5]); o.w = pk2(v[6], v[7]); return o; }
; __device__ __forceinline__ void prep_task(LAS unsigned char* lds, const PrepP& P, int task, int tid, int lane, int wave) {
;     ...
;         { float sq = 0.f;
; #pragma unroll
;           for (int i = 0; i < 16; ++i) sq += x[i] * x[i];
;           sq += __shfl_xor(sq, 1); sq += __shfl_xor(sq, 2); sq += __shfl_xor(sq, 4);
;           const float rq = rsq_f(sq + EPS) * 0.08838834764831845f;
; #pragma unroll
;           for (int i = 0; i < 16; ++i) x[i] *= rq; }
;         *(LAS u32x4*)(Ql + lo) = pack8(x); *(LAS u32x4*)(Ql + lo + 8) = pack8(x + 8);
; #pragma unroll
;         for (int i = 0; i < 16; ++i) y[i] = x[i] * eg;
;         bf16_t* qo = (bf16_t*)(trp + TR_Q) + t * 128 + seg * 16;
;         *(u32x4*)qo = pack8(y); *(u32x4*)(qo + 8) = pack8(y + 8);
;     }
;     LBAR();
;     {
;         const int it = wave >> 1, jt0 = (wave & 1) * 2;
;         bf16x8 aK[4], aQ[4];
; #pragma unroll
;         for (int ks = 0; ks < 4; ++ks) { aK[ks] = *(const LAS bf16x8*)(Kl + (it * 16 + r) * PS + ks * 32 + q8 * 8); aQ[ks] = *(const LAS bf16x8*)(Ql + (it * 16 + r) * PS + ks * 32 + q8 * 8); }
	v_pk_fma_f32 v[0:1], v[68:69], v[4:5], v[0:1]
	v_mul_f32_e32 v17, v17, v7
	v_mul_f32_e32 v18, v6, v18
	v_mul_f32_e32 v4, 0xbfb8aa3b, v0
	v_mul_f32_e32 v5, 0xbfb8aa3b, v1
	v_and_b32_e32 v7, 0xffff0000, v24
	v_lshlrev_b32_e32 v6, 16, v24
	v_exp_f32_e32 v4, v4
	v_exp_f32_e32 v5, v5
	v_pk_fma_f32 v[2:3], v[2:3], v[6:7], 0 op_sel_hi:[1,1,0]
	v_and_b32_e32 v7, 0xffff0000, v15
	v_lshlrev_b32_e32 v6, 16, v15
	v_pk_fma_f32 v[2:3], v[34:35], v[6:7], v[2:3]
	v_and_b32_e32 v7, 0xffff0000, v11
	v_lshlrev_b32_e32 v6, 16, v11
	v_mul_f32_e32 v21, v25, v25
	v_pk_fma_f32 v[2:3], v[52:53], v[6:7], v[2:3]
	v_and_b32_e32 v7, 0xffff0000, v12
	v_lshlrev_b32_e32 v6, 16, v12
	v_fmac_f32_e32 v21, v9, v9
	v_pk_fma_f32 v[2:3], v[70:71], v[6:7], v[2:3]
	v_fmac_f32_e32 v21, v29, v29
	v_add_f32_e32 v4, 1.0, v4
	v_add_f32_e32 v5, 1.0, v5
	v_mul_f32_e32 v6, 0xbfb8aa3b, v2
	v_mul_f32_e32 v7, 0xbfb8aa3b, v3
	v_fmac_f32_e32 v21, v49, v49
	v_rcp_f32_e32 v4, v4
	v_rcp_f32_e32 v5, v5
	v_exp_f32_e32 v6, v6
	v_exp_f32_e32 v7, v7
	v_fmac_f32_e32 v21, v61, v61
	v_fmac_f32_e32 v21, v72, v72
	v_fmac_f32_e32 v21, v73, v73
	v_fmac_f32_e32 v21, v74, v74
	v_pk_mul_f32 v[0:1], v[0:1], v[4:5]
	v_add_f32_e32 v4, 1.0, v6
	v_add_f32_e32 v5, 1.0, v7
	v_fmac_f32_e32 v21, v20, v20
	v_rcp_f32_e32 v4, v4
	v_rcp_f32_e32 v5, v5
	v_fmac_f32_e32 v21, v17, v17
	v_fmac_f32_e32 v21, v18, v18
	v_fmac_f32_e32 v21, v19, v19
	v_pk_mul_f32 v[6:7], v[0:1], v[0:1]
	v_pk_mul_f32 v[2:3], v[2:3], v[4:5]
	v_add_f32_e32 v6, v6, v21
	v_add_f32_e32 v6, v7, v6
	v_pk_mul_f32 v[4:5], v[2:3], v[2:3]
	s_mov_b32 s6, 0x22404000
	v_add_f32_e32 v4, v4, v6
	v_add_f32_e32 v4, v5, v4
	ds_bpermute_b32 v5, v16, v4
	v_and_b32_e32 v59, 15, v55
	v_or_b32_e32 v65, s34, v59
	v_lshlrev_b32_e32 v32, 6, v65
	v_ashrrev_i32_e32 v33, 31, v32
	s_waitcnt lgkmcnt(0)
	v_add_f32_e32 v4, v4, v5
	ds_bpermute_b32 v5, v13, v4
	v_lshrrev_b32_e32 v62, 4, v56
	v_lshlrev_b64 v[32:33], 1, v[32:33]
	v_lshlrev_b32_e32 v75, 2, v62
	v_add_u32_e32 v64, 0x15400, v58
	s_waitcnt lgkmcnt(0)
	v_add_f32_e32 v4, v4, v5
	ds_bpermute_b32 v5, v10, v4
	v_lshl_add_u32 v66, v65, 2, v63
	s_waitcnt lgkmcnt(0)
	v_add_f32_e32 v4, v4, v5
	v_add_f32_e32 v4, 0x358637bd, v4
	v_rsq_f32_e32 v4, v4
	s_nop 0
	v_mul_f32_e32 v4, 0x3db504f3, v4
	v_mul_f32_e32 v5, v9, v4
	v_mul_f32_e32 v6, v25, v4
	v_mul_f32_e32 v16, v18, v4
	v_mul_f32_e32 v18, v0, v4
	v_cvt_pk_bf16_f32 v0, v5, v6
	v_mul_f32_e32 v7, v29, v4
	v_mul_f32_e32 v9, v49, v4
	v_mul_f32_e32 v10, v61, v4
	v_mul_f32_e32 v11, v72, v4
	v_mul_f32_e32 v12, v73, v4
	v_mul_f32_e32 v13, v74, v4
	v_mul_f32_e32 v14, v20, v4
	v_mul_f32_e32 v15, v17, v4
	v_mul_f32_e32 v17, v19, v4
	v_mul_f32_e32 v19, v1, v4
	v_mul_f32_e32 v20, v2, v4
	v_mul_f32_e32 v4, v3, v4
	v_cvt_pk_bf16_f32 v1, v7, v9
	v_cvt_pk_bf16_f32 v2, v10, v11
	v_cvt_pk_bf16_f32 v3, v12, v13
	ds_write_b128 v60, v[0:3] offset:17408
	v_cvt_pk_bf16_f32 v0, v14, v15
	v_cvt_pk_bf16_f32 v1, v16, v17
	v_cvt_pk_bf16_f32 v2, v18, v19
	v_cvt_pk_bf16_f32 v3, v20, v4
	ds_write_b128 v60, v[0:3] offset:17424
	v_lshlrev_b32_e32 v0, 7, v26
	v_ashrrev_i32_e32 v1, 31, v0
	v_mul_f32_e32 v2, v8, v5
	v_mul_f32_e32 v3, v8, v6
	v_mul_f32_e32 v6, v8, v7
	v_mul_f32_e32 v7, v8, v9
	v_mul_f32_e32 v9, v8, v10
	v_mul_f32_e32 v10, v8, v11
	v_mul_f32_e32 v11, v8, v12
	v_mul_f32_e32 v12, v8, v13
	v_mul_f32_e32 v13, v8, v14
	v_mul_f32_e32 v14, v8, v15
	v_mul_f32_e32 v15, v8, v16
	v_mul_f32_e32 v16, v8, v17
	v_mul_f32_e32 v17, v8, v18
	v_mul_f32_e32 v18, v8, v19
	v_mul_f32_e32 v19, v8, v20
	v_mul_f32_e32 v8, v8, v4
	v_and_b32_e32 v4, 7, v55
	v_lshlrev_b64 v[0:1], 1, v[0:1]
	v_lshl_or_b32 v0, v4, 5, v0
	v_lshl_add_u64 v[0:1], s[26:27], 0, v[0:1]
	v_lshl_add_u64 v[4:5], v[40:41], 0, v[0:1]
	v_add_co_u32_e32 v4, vcc, s6, v4
	v_cvt_pk_bf16_f32 v0, v2, v3
	v_cvt_pk_bf16_f32 v1, v6, v7
	v_cvt_pk_bf16_f32 v2, v9, v10
	v_cvt_pk_bf16_f32 v3, v11, v12
	s_nop 1
	v_addc_co_u32_e32 v5, vcc, 0, v5, vcc
	global_store_dwordx4 v[4:5], v[0:3], off
	v_and_b32_e32 v61, 48, v55
	v_lshrrev_b32_e32 v60, 1, v61
	v_cvt_pk_bf16_f32 v0, v13, v14
	v_cvt_pk_bf16_f32 v1, v15, v16
	v_cvt_pk_bf16_f32 v2, v17, v18
	v_cvt_pk_bf16_f32 v3, v19, v8
	global_store_dwordx4 v[4:5], v[0:3], off offset:16
	s_waitcnt lgkmcnt(0)
	s_barrier
	v_or_b32_e32 v32, v32, v60
	v_mul_lo_u32 v0, v65, s51
	v_and_b32_e32 v1, 48, v56
	v_add3_u32 v12, v58, v0, v1
	ds_read_b128 v[24:27], v12
	ds_read_b128 v[4:7], v12 offset:64
	ds_read_b128 v[28:31], v12 offset:17408
	ds_read_b128 v[16:19], v12 offset:17472
	ds_read_b128 v[8:11], v12 offset:128
	ds_read_b128 v[0:3], v12 offset:192
	ds_read_b128 v[20:23], v12 offset:17536
	ds_read_b128 v[12:15], v12 offset:17600
	v_or_b32_e32 v72, s34, v75
	v_lshl_add_u64 v[32:33], s[28:29], 0, v[32:33]
	v_lshl_add_u64 v[50:51], v[40:41], 0, v[32:33]
	s_mov_b64 s[6:7], 0x22408000
	v_or_b32_e32 v71, 1, v72
	v_or_b32_e32 v69, 2, v72
	v_or_b32_e32 v67, 3, v72
	v_add_u32_e32 v76, v58, v61
	v_lshl_add_u64 v[52:53], v[50:51], 0, s[6:7]
	s_mov_b64 s[6:7], -1
	s_andn2_b64 vcc, exec, s[18:19]
	v_lshl_add_u32 v74, v72, 2, v63
	v_lshl_add_u32 v73, v71, 2, v63
	v_lshl_add_u32 v70, v69, 2, v63
	v_lshl_add_u32 v68, v67, 2, v63
	s_cbranch_vccz .LBB0_427
	v_lshl_add_u32 v33, v59, 2, v64
	s_andn2_b64 vcc, exec, s[6:7]
	v_lshlrev_b32_e32 v32, 8, v72
	s_cbranch_vccz .LBB0_428
